# up-projection epilogues: 8 serialized row-rstd loads (load, vmcnt(0), reduce) prefetched up front with counted waits; conversion ticket atomic no longer waited at ticket start
# speedup vs baseline: 1.0095x; 1.0095x over previous
; __device__ __forceinline__ float sum4(f32x4 a) { return (a[0] + a[1]) + (a[2] + a[3]); }
; __device__ __forceinline__ float red_fq(float s) { s += swz16(s); return half_sum(s); }
; template <int N4, int STRIDE> __device__ __forceinline__ void row_rstd(float (&rs)[2][4], const float* slots, int row0, float invdim, int fq) {
; #pragma unroll
;     for (int ai = 0; ai < 2; ++ai)
; #pragma unroll
;         for (int m = 0; m < 4; ++m) { const f32x4* s = (const f32x4*)(slots + (size_t)(row0 + ai * 128 + m * 16) * STRIDE);
;             float t = (fq < N4) ? sum4(s[fq < N4 ? fq : 0]) : 0.f;
;             t = red_fq(t);
;             rs[ai][m] = rsqrtf(t * invdim + EPS); }
;     __device__ __forceinline__ void operator()(AccRef acc, const pg8::Unit& u, int wr, int wc, int fr, int fq) const {
;     ...
;         float rs[2][4]; row_rstd<3, 32>(rs, ssqd, row0, 1.0f / 384.0f, fq);
.LBB0_376:
	v_mbcnt_lo_u32_b32 v0, -1, 0
	v_mbcnt_hi_u32_b32 v0, -1, v0
	s_lshl_b32 s0, s71, 8
	s_add_i32 s0, s0, s65
	v_ashrrev_i32_e32 v138, 4, v0
	v_and_or_b32 v170, v0, 15, s0
	v_ashrrev_i32_e32 v139, 31, v138
	v_cmp_gt_i32_e64 s[0:1], 3, v138
	v_lshl_add_u64 v[130:131], v[138:139], 4, s[30:31]
	v_mov_b32_e32 v133, 0
	v_ashrrev_i32_e32 v171, 31, v170
	v_mov_b32_e32 v0, 0
	s_and_saveexec_b64 s[52:53], s[0:1]
	v_lshlrev_b64 v[202:203], 7, v[170:171]
	v_lshl_add_u64 v[202:203], v[130:131], 0, v[202:203]
	v_add_co_u32_e32 v206, vcc, 0x1000, v202
	s_nop 1
	v_addc_co_u32_e32 v207, vcc, 0, v203, vcc
	v_add_co_u32_e32 v210, vcc, 0x4000, v202
	s_nop 1
	v_addc_co_u32_e32 v211, vcc, 0, v203, vcc
	v_add_co_u32_e32 v214, vcc, 0x5000, v202
	s_nop 1
	v_addc_co_u32_e32 v215, vcc, 0, v203, vcc
	global_load_dwordx4 v[218:221], v[202:203], off
	global_load_dwordx4 v[202:205], v[202:203], off offset:2048
	global_load_dwordx4 v[226:229], v[206:207], off
	global_load_dwordx4 v[206:209], v[206:207], off offset:2048
	global_load_dwordx4 v[238:241], v[210:211], off
	global_load_dwordx4 v[210:213], v[210:211], off offset:2048
	global_load_dwordx4 v[242:245], v[214:215], off
	global_load_dwordx4 v[214:217], v[214:215], off offset:2048
	s_or_b64 exec, exec, s[52:53]
	s_and_saveexec_b64 s[52:53], s[0:1]
	s_cbranch_execz .LBB0_378
	s_waitcnt vmcnt(7)
	v_mov_b32_e32 v134, v218
	v_mov_b32_e32 v135, v219
	v_mov_b32_e32 v136, v220
	v_mov_b32_e32 v137, v221
	v_mov_b32_e32 v140, v135
	v_mov_b32_e32 v141, v136
	v_mov_b32_e32 v135, v137
	v_pk_add_f32 v[134:135], v[140:141], v[134:135]
	s_nop 0
	v_add_f32_e32 v0, v134, v135
.LBB0_378:
	s_or_b64 exec, exec, s[52:53]
	ds_swizzle_b32 v132, v0 offset:swizzle(SWAP,16)
	v_or_b32_e32 v182, 16, v170
	s_waitcnt lgkmcnt(0)
	v_add_f32_e32 v0, v0, v132
	v_mov_b32_e32 v132, v0
	s_nop 1
	v_permlane32_swap_b32_e32 v0, v132
	s_mov_b64 s[52:53], exec
	s_and_b64 s[54:55], s[52:53], s[0:1]
	v_mov_b64_e32 v[248:249], v[172:173]
	s_mov_b64 exec, s[54:55]
	s_cbranch_execz .LBB0_380
	v_ashrrev_i32_e32 v183, 31, v182
	s_waitcnt vmcnt(6)
	v_mov_b32_e32 v134, v202
	v_mov_b32_e32 v135, v203
	v_mov_b32_e32 v136, v204
	v_mov_b32_e32 v137, v205
	v_mov_b32_e32 v140, v135
	v_mov_b32_e32 v141, v136
	v_mov_b32_e32 v135, v137
	v_pk_add_f32 v[134:135], v[140:141], v[134:135]
	s_nop 0
	v_add_f32_e32 v133, v134, v135
.LBB0_380:
	s_or_b64 exec, exec, s[52:53]
	ds_swizzle_b32 v134, v133 offset:swizzle(SWAP,16)
	v_mov_b32_e32 v137, 0
	v_or_b32_e32 v176, 32, v170
	v_mov_b32_e32 v135, 0
	s_waitcnt lgkmcnt(0)
	v_add_f32_e32 v133, v133, v134
	v_mov_b32_e32 v134, v133
	s_nop 1
	v_permlane32_swap_b32_e32 v133, v134
	s_and_saveexec_b64 s[52:53], s[0:1]
	s_cbranch_execz .LBB0_382
	v_ashrrev_i32_e32 v177, 31, v176
	s_waitcnt vmcnt(5)
	v_mov_b32_e32 v140, v226
	v_mov_b32_e32 v141, v227
	v_mov_b32_e32 v142, v228
	v_mov_b32_e32 v143, v229
	v_mov_b32_e32 v144, v141
	v_mov_b32_e32 v145, v142
	v_mov_b32_e32 v141, v143
	v_pk_add_f32 v[140:141], v[144:145], v[140:141]
	s_nop 0
	v_add_f32_e32 v135, v140, v141
.LBB0_382:
	s_or_b64 exec, exec, s[52:53]
	ds_swizzle_b32 v136, v135 offset:swizzle(SWAP,16)
	v_or_b32_e32 v174, 48, v170
	s_waitcnt lgkmcnt(0)
	v_add_f32_e32 v135, v135, v136
	v_mov_b32_e32 v136, v135
	s_nop 1
	v_permlane32_swap_b32_e32 v135, v136
	s_and_saveexec_b64 s[52:53], s[0:1]
	s_cbranch_execz .LBB0_384
	v_ashrrev_i32_e32 v175, 31, v174
	s_waitcnt vmcnt(4)
	v_mov_b32_e32 v140, v206
	v_mov_b32_e32 v141, v207
	v_mov_b32_e32 v142, v208
	v_mov_b32_e32 v143, v209
	v_mov_b32_e32 v144, v141
	v_mov_b32_e32 v145, v142
	v_mov_b32_e32 v141, v143
	v_pk_add_f32 v[140:141], v[144:145], v[140:141]
	s_nop 0
	v_add_f32_e32 v137, v140, v141
.LBB0_384:
	s_or_b64 exec, exec, s[52:53]
	ds_swizzle_b32 v139, v137 offset:swizzle(SWAP,16)
	v_mov_b32_e32 v143, 0
	s_waitcnt lgkmcnt(0)
	v_add_f32_e32 v139, v137, v139
	v_mov_b32_e32 v140, v139
	s_nop 1
	v_permlane32_swap_b32_e32 v139, v140
	v_mov_b32_e32 v137, 0
	s_and_saveexec_b64 s[52:53], s[0:1]
	s_cbranch_execz .LBB0_386
	s_waitcnt vmcnt(3)
	v_mov_b32_e32 v144, v238
	v_mov_b32_e32 v145, v239
	v_mov_b32_e32 v146, v240
	v_mov_b32_e32 v147, v241
	v_mov_b32_e32 v148, v145
	v_mov_b32_e32 v149, v146
	v_mov_b32_e32 v145, v147
	v_pk_add_f32 v[144:145], v[148:149], v[144:145]
	s_nop 0
	v_add_f32_e32 v137, v144, v145
.LBB0_386:
	s_or_b64 exec, exec, s[52:53]
	ds_swizzle_b32 v141, v137 offset:swizzle(SWAP,16)
	s_waitcnt lgkmcnt(0)
	v_add_f32_e32 v141, v137, v141
	v_mov_b32_e32 v142, v141
	s_nop 1
	v_permlane32_swap_b32_e32 v141, v142
	s_and_saveexec_b64 s[52:53], s[0:1]
	s_cbranch_execz .LBB0_388
	s_waitcnt vmcnt(2)
	v_mov_b32_e32 v144, v210
	v_mov_b32_e32 v145, v211
	v_mov_b32_e32 v146, v212
	v_mov_b32_e32 v147, v213
	v_mov_b32_e32 v148, v145
	v_mov_b32_e32 v149, v146
	v_mov_b32_e32 v145, v147
	v_pk_add_f32 v[144:145], v[148:149], v[144:145]
	s_nop 0
	v_add_f32_e32 v143, v144, v145
.LBB0_388:
	s_or_b64 exec, exec, s[52:53]
	ds_swizzle_b32 v144, v143 offset:swizzle(SWAP,16)
	v_mov_b32_e32 v137, 0
	v_mov_b32_e32 v145, 0
	s_waitcnt lgkmcnt(0)
	v_add_f32_e32 v143, v143, v144
	v_mov_b32_e32 v144, v143
	s_nop 1
	v_permlane32_swap_b32_e32 v143, v144
	s_and_saveexec_b64 s[52:53], s[0:1]
	s_cbranch_execz .LBB0_390
	s_waitcnt vmcnt(1)
	v_mov_b32_e32 v146, v242
	v_mov_b32_e32 v147, v243
	v_mov_b32_e32 v148, v244
	v_mov_b32_e32 v149, v245
	v_mov_b32_e32 v150, v147
	v_mov_b32_e32 v151, v148
	v_mov_b32_e32 v147, v149
	v_pk_add_f32 v[146:147], v[150:151], v[146:147]
	s_nop 0
	v_add_f32_e32 v145, v146, v147
.LBB0_390:
	s_or_b64 exec, exec, s[52:53]
	ds_swizzle_b32 v146, v145 offset:swizzle(SWAP,16)
	s_waitcnt lgkmcnt(0)
	v_add_f32_e32 v145, v145, v146
	v_mov_b32_e32 v146, v145
	s_nop 1
	v_permlane32_swap_b32_e32 v145, v146
	s_and_saveexec_b64 s[52:53], s[0:1]
	s_cbranch_execz .LBB0_392
	s_waitcnt vmcnt(0)
	v_mov_b32_e32 v148, v214
	v_mov_b32_e32 v149, v215
	v_mov_b32_e32 v150, v216
	v_mov_b32_e32 v151, v217
	v_mov_b32_e32 v130, v149
	v_mov_b32_e32 v131, v150
	v_mov_b32_e32 v149, v151
	v_pk_add_f32 v[130:131], v[130:131], v[148:149]
	s_nop 0
	v_add_f32_e32 v137, v130, v131

; __device__ __forceinline__ float sum4(f32x4 a) { return (a[0] + a[1]) + (a[2] + a[3]); }
; __device__ __forceinline__ float red_fq(float s) { s += swz16(s); return half_sum(s); }
; template <int N4, int STRIDE> __device__ __forceinline__ void row_rstd(float (&rs)[2][4], const float* slots, int row0, float invdim, int fq) {
; #pragma unroll
;     for (int ai = 0; ai < 2; ++ai)
; #pragma unroll
;         for (int m = 0; m < 4; ++m) { const f32x4* s = (const f32x4*)(slots + (size_t)(row0 + ai * 128 + m * 16) * STRIDE);
;             float t = (fq < N4) ? sum4(s[fq < N4 ? fq : 0]) : 0.f;
;             t = red_fq(t);
;             rs[ai][m] = rsqrtf(t * invdim + EPS); }
;     __device__ __forceinline__ void operator()(AccRef acc, const pg8::Unit& u, int wr, int wc, int fr, int fq) const {
;     ...
;         float rs[2][4]; row_rstd<2, 32>(rs, ssqd + 12, row0, 1.0f / 256.0f, fq);
.LBB0_414:
	v_mbcnt_lo_u32_b32 v131, -1, 0
	v_mbcnt_hi_u32_b32 v131, -1, v131
	s_lshl_b32 s4, s70, 8
	s_add_i32 s4, s4, s64
	v_ashrrev_i32_e32 v130, 4, v131
	v_and_or_b32 v166, v131, 15, s4
	v_ashrrev_i32_e32 v131, 31, v130
	v_cmp_gt_i32_e64 s[4:5], 2, v130
	v_lshl_add_u64 v[132:133], v[130:131], 4, s[40:41]
	v_mov_b32_e32 v135, 0
	v_ashrrev_i32_e32 v167, 31, v166
	v_mov_b32_e32 v131, 0
	s_and_saveexec_b64 s[52:53], s[4:5]
	v_lshlrev_b64 v[198:199], 7, v[166:167]
	v_lshl_add_u64 v[198:199], v[132:133], 0, v[198:199]
	v_add_co_u32_e32 v206, vcc, 0x1000, v198
	s_nop 1
	v_addc_co_u32_e32 v207, vcc, 0, v199, vcc
	v_add_co_u32_e32 v214, vcc, 0x4000, v198
	s_nop 1
	v_addc_co_u32_e32 v215, vcc, 0, v199, vcc
	v_add_co_u32_e32 v222, vcc, 0x5000, v198
	s_nop 1
	v_addc_co_u32_e32 v223, vcc, 0, v199, vcc
	global_load_dwordx4 v[202:205], v[198:199], off
	global_load_dwordx4 v[198:201], v[198:199], off offset:2048
	global_load_dwordx4 v[210:213], v[206:207], off
	global_load_dwordx4 v[206:209], v[206:207], off offset:2048
	global_load_dwordx4 v[218:221], v[214:215], off
	global_load_dwordx4 v[214:217], v[214:215], off offset:2048
	global_load_dwordx4 v[226:229], v[222:223], off
	global_load_dwordx4 v[222:225], v[222:223], off offset:2048
	s_or_b64 exec, exec, s[52:53]
	s_and_saveexec_b64 s[52:53], s[4:5]
	s_cbranch_execz .LBB0_416
	s_waitcnt vmcnt(7)
	v_mov_b32_e32 v136, v202
	v_mov_b32_e32 v137, v203
	v_mov_b32_e32 v138, v204
	v_mov_b32_e32 v139, v205
	v_mov_b32_e32 v140, v137
	v_mov_b32_e32 v141, v138
	v_mov_b32_e32 v137, v139
	v_pk_add_f32 v[136:137], v[140:141], v[136:137]
	s_nop 0
	v_add_f32_e32 v131, v136, v137
.LBB0_416:
	s_or_b64 exec, exec, s[52:53]
	ds_swizzle_b32 v134, v131 offset:swizzle(SWAP,16)
	v_or_b32_e32 v164, 16, v166
	v_ashrrev_i32_e32 v165, 31, v164
	s_waitcnt lgkmcnt(0)
	v_add_f32_e32 v131, v131, v134
	v_mov_b32_e32 v134, v131
	s_nop 1
	v_permlane32_swap_b32_e32 v131, v134
	s_and_saveexec_b64 s[52:53], s[4:5]
	s_cbranch_execz .LBB0_418
	s_waitcnt vmcnt(6)
	v_mov_b32_e32 v136, v198
	v_mov_b32_e32 v137, v199
	v_mov_b32_e32 v138, v200
	v_mov_b32_e32 v139, v201
	v_mov_b32_e32 v140, v137
	v_mov_b32_e32 v141, v138
	v_mov_b32_e32 v137, v139
	v_pk_add_f32 v[136:137], v[140:141], v[136:137]
	s_nop 0
	v_add_f32_e32 v135, v136, v137
.LBB0_418:
	s_or_b64 exec, exec, s[52:53]
	ds_swizzle_b32 v136, v135 offset:swizzle(SWAP,16)
	v_or_b32_e32 v156, 32, v166
	v_mov_b32_e32 v139, 0
	v_ashrrev_i32_e32 v157, 31, v156
	v_mov_b32_e32 v137, 0
	s_waitcnt lgkmcnt(0)
	v_add_f32_e32 v135, v135, v136
	v_mov_b32_e32 v136, v135
	s_nop 1
	v_permlane32_swap_b32_e32 v135, v136
	s_and_saveexec_b64 s[52:53], s[4:5]
	s_cbranch_execz .LBB0_420
	s_waitcnt vmcnt(5)
	v_mov_b32_e32 v140, v210
	v_mov_b32_e32 v141, v211
	v_mov_b32_e32 v142, v212
	v_mov_b32_e32 v143, v213
	v_mov_b32_e32 v144, v141
	v_mov_b32_e32 v145, v142
	v_mov_b32_e32 v141, v143
	v_pk_add_f32 v[140:141], v[144:145], v[140:141]
	s_nop 0
	v_add_f32_e32 v137, v140, v141
.LBB0_420:
	s_or_b64 exec, exec, s[52:53]
	ds_swizzle_b32 v138, v137 offset:swizzle(SWAP,16)
	v_or_b32_e32 v154, 48, v166
	v_ashrrev_i32_e32 v155, 31, v154
	s_waitcnt lgkmcnt(0)
	v_add_f32_e32 v137, v137, v138
	v_mov_b32_e32 v138, v137
	s_nop 1
	v_permlane32_swap_b32_e32 v137, v138
	s_and_saveexec_b64 s[52:53], s[4:5]
	s_cbranch_execz .LBB0_422
	s_waitcnt vmcnt(4)
	v_mov_b32_e32 v140, v206
	v_mov_b32_e32 v141, v207
	v_mov_b32_e32 v142, v208
	v_mov_b32_e32 v143, v209
	v_mov_b32_e32 v144, v141
	v_mov_b32_e32 v145, v142
	v_mov_b32_e32 v141, v143
	v_pk_add_f32 v[140:141], v[144:145], v[140:141]
	s_nop 0
	v_add_f32_e32 v139, v140, v141
.LBB0_422:
	s_or_b64 exec, exec, s[52:53]
	ds_swizzle_b32 v140, v139 offset:swizzle(SWAP,16)
	v_mov_b32_e32 v144, 0
	s_waitcnt lgkmcnt(0)
	v_add_f32_e32 v140, v139, v140
	v_mov_b32_e32 v141, v140
	s_nop 1
	v_permlane32_swap_b32_e32 v140, v141
	v_mov_b32_e32 v139, 0
	s_and_saveexec_b64 s[52:53], s[4:5]
	s_cbranch_execz .LBB0_424
	s_waitcnt vmcnt(3)
	v_mov_b32_e32 v160, v218
	v_mov_b32_e32 v161, v219
	v_mov_b32_e32 v162, v220
	v_mov_b32_e32 v163, v221
	v_mov_b32_e32 v142, v161
	v_mov_b32_e32 v143, v162
	v_mov_b32_e32 v161, v163
	v_pk_add_f32 v[142:143], v[142:143], v[160:161]
	s_nop 0
	v_add_f32_e32 v139, v142, v143
.LBB0_424:
	s_or_b64 exec, exec, s[52:53]
	ds_swizzle_b32 v142, v139 offset:swizzle(SWAP,16)
	s_waitcnt lgkmcnt(0)
	v_add_f32_e32 v142, v139, v142
	v_mov_b32_e32 v143, v142
	s_nop 1
	v_permlane32_swap_b32_e32 v142, v143
	s_and_saveexec_b64 s[52:53], s[4:5]
	s_cbranch_execz .LBB0_426
	s_waitcnt vmcnt(2)
	v_mov_b32_e32 v160, v214
	v_mov_b32_e32 v161, v215
	v_mov_b32_e32 v162, v216
	v_mov_b32_e32 v163, v217
	v_mov_b32_e32 v144, v161
	v_mov_b32_e32 v145, v162
	v_mov_b32_e32 v161, v163
	v_pk_add_f32 v[144:145], v[144:145], v[160:161]
	s_nop 0
	v_add_f32_e32 v144, v144, v145
.LBB0_426:
	s_or_b64 exec, exec, s[52:53]
	ds_swizzle_b32 v145, v144 offset:swizzle(SWAP,16)
	v_mov_b32_e32 v139, 0
	v_mov_b32_e32 v152, 0
	s_waitcnt lgkmcnt(0)
	v_add_f32_e32 v144, v144, v145
	v_mov_b32_e32 v145, v144
	s_nop 1
	v_permlane32_swap_b32_e32 v144, v145
	s_and_saveexec_b64 s[52:53], s[4:5]
	s_cbranch_execz .LBB0_428
	s_waitcnt vmcnt(1)
	v_mov_b32_e32 v160, v226
	v_mov_b32_e32 v161, v227
	v_mov_b32_e32 v162, v228
	v_mov_b32_e32 v163, v229
	v_mov_b32_e32 v168, v161
	v_mov_b32_e32 v169, v162
	v_mov_b32_e32 v161, v163
	v_pk_add_f32 v[160:161], v[168:169], v[160:161]
	s_nop 0
	v_add_f32_e32 v152, v160, v161
.LBB0_428:
	s_or_b64 exec, exec, s[52:53]
	ds_swizzle_b32 v158, v152 offset:swizzle(SWAP,16)
	s_waitcnt lgkmcnt(0)
	v_add_f32_e32 v152, v152, v158
	v_mov_b32_e32 v158, v152
	s_nop 1
	v_permlane32_swap_b32_e32 v152, v158
	s_and_saveexec_b64 s[52:53], s[4:5]
	s_cbranch_execz .LBB0_430
	s_waitcnt vmcnt(0)
	v_mov_b32_e32 v160, v222
	v_mov_b32_e32 v161, v223
	v_mov_b32_e32 v162, v224
	v_mov_b32_e32 v163, v225
	v_mov_b32_e32 v132, v161
	v_mov_b32_e32 v133, v162
	v_mov_b32_e32 v161, v163
	v_pk_add_f32 v[132:133], v[132:133], v[160:161]
	s_nop 0
	v_add_f32_e32 v139, v132, v133

; #define LAS __attribute__((address_space(3)))
; __device__ __forceinline__ void conv_item(const float* W, int K, int Nsrc, int Ndst, const float* ksc, bf16* WT, int map, int item, LAS float* scr, int lane) {
;     const int nblk = Ndst / 32, kb = item / nblk, nb = item % nblk, k0 = 64 * kb, n0 = 32 * nb;
;     const int sc = src_col(map, n0 + (lane & 31));
;     float wv[32];
;     { const float* wp = W + (size_t)(k0 + (lane >> 5)) * Nsrc + (sc >= 0 ? sc : 0);
; #pragma unroll
;       for (int i = 0; i < 32; ++i) wv[i] = wp[(size_t)(2 * i) * Nsrc]; }
; __global__ void __launch_bounds__(512, 2) fwd_kernel(Args a) {
;     ...
;                 while (ti < CV_TICKETS) { unsigned nxc = 0u; if (tid == 0) nxc = atomicAdd(cq, 1u);
;                     conv_ticket(cs, wd, ti, lds, wave);
.LBB0_442:
	s_waitcnt lgkmcnt(0)
	v_mov_b32_e32 v6, 0
	s_and_saveexec_b64 s[0:1], s[40:41]
	s_cbranch_execz .LBB0_446
	s_mov_b64 s[52:53], exec
	v_mbcnt_lo_u32_b32 v0, s52, 0
	v_mbcnt_hi_u32_b32 v0, s53, v0
	v_cmp_eq_u32_e32 vcc, 0, v0
	s_and_saveexec_b64 s[50:51], vcc
	s_cbranch_execz .LBB0_445
	s_bcnt1_i32_b64 s52, s[52:53]
	v_mov_b32_e32 v2, s52
	global_atomic_add v6, v1, v2, s[4:5] offset:32 sc0
.LBB0_445:
	s_or_b64 exec, exec, s[50:51]
.LBB0_446:
	s_or_b64 exec, exec, s[0:1]
	s_mov_b64 s[0:1], 0
	s_add_u32 s58, s3, s0
	s_addc_u32 s59, s33, s1
	s_lshl_b32 s50, s44, 3
	s_add_i32 s50, s50, s2
	s_cmpk_gt_i32 s50, 0xd7f
	s_mov_b64 s[0:1], -1
	v_mbcnt_lo_u32_b32 v7, -1, 0
	v_mbcnt_hi_u32_b32 v7, -1, v7
	s_cbranch_scc0 .LBB0_479
	s_cmpk_gt_u32 s50, 0xe0f
	s_cbranch_scc0 .LBB0_471
	s_cmpk_gt_u32 s50, 0xe8f
	s_cbranch_scc0 .LBB0_464
	s_cmpk_gt_u32 s50, 0x118f
	s_cbranch_scc0 .LBB0_461
	s_cmpk_gt_u32 s50, 0x138f
	s_cbranch_scc0 .LBB0_458
	s_cmpk_gt_u32 s50, 0x1b8f
	s_cbranch_scc0 .LBB0_455
	s_cmpk_gt_u32 s50, 0x238f
	s_cbranch_scc1 .LBB0_454
	s_add_i32 s0, s50, 0xffffe470
	s_lshl_b32 s1, s0, 1
	s_and_b32 s1, s1, 0x1ffc0
	v_ashrrev_i32_e32 v9, 5, v7
	s_lshl_b32 s0, s0, 5
	v_add_u32_e32 v2, s1, v9
	s_and_b32 s0, s0, 0x3e0
	v_and_b32_e32 v8, 31, v7
	v_ashrrev_i32_e32 v3, 31, v2
	v_or_b32_e32 v0, s0, v8
	v_lshlrev_b64 v[2:3], 12, v[2:3]
	v_lshl_add_u64 v[2:3], s[48:49], 0, v[2:3]
	v_lshlrev_b32_e32 v0, 2, v0
	v_lshl_add_u64 v[2:3], v[2:3], 0, v[0:1]
	s_movk_i32 s27, 0x2000
	v_add_co_u32_e32 v4, vcc, s27, v2
	s_movk_i32 s27, 0x4000
	s_nop 0
	v_addc_co_u32_e32 v5, vcc, 0, v3, vcc
	global_load_dword v0, v[2:3], off
	global_load_dword v10, v[4:5], off
	v_add_co_u32_e32 v4, vcc, s27, v2
	s_movk_i32 s27, 0x6000
	s_nop 0
	v_addc_co_u32_e32 v5, vcc, 0, v3, vcc
	global_load_dword v11, v[4:5], off
	v_add_co_u32_e32 v4, vcc, s27, v2
	s_mov_b32 s27, 0x8000
	s_nop 0
	v_addc_co_u32_e32 v5, vcc, 0, v3, vcc
	global_load_dword v12, v[4:5], off
	v_add_co_u32_e32 v4, vcc, s27, v2
	s_mov_b32 s27, 0xa000
	s_nop 0
	v_addc_co_u32_e32 v5, vcc, 0, v3, vcc
	global_load_dword v13, v[4:5], off
	v_add_co_u32_e32 v4, vcc, s27, v2
	s_mov_b32 s27, 0xc000
	s_nop 0
	v_addc_co_u32_e32 v5, vcc, 0, v3, vcc
	global_load_dword v14, v[4:5], off
	v_add_co_u32_e32 v4, vcc, s27, v2
	s_mov_b32 s27, 0xe000
	s_nop 0
	v_addc_co_u32_e32 v5, vcc, 0, v3, vcc
	global_load_dword v15, v[4:5], off
	v_add_co_u32_e32 v4, vcc, s27, v2
	s_mov_b32 s27, 0x10000
	s_nop 0
	v_addc_co_u32_e32 v5, vcc, 0, v3, vcc
	global_load_dword v16, v[4:5], off
	v_add_co_u32_e32 v4, vcc, s27, v2
	s_mov_b32 s27, 0x12000
	s_nop 0
	v_addc_co_u32_e32 v5, vcc, 0, v3, vcc
	global_load_dword v17, v[4:5], off
	v_add_co_u32_e32 v4, vcc, s27, v2
	s_mov_b32 s27, 0x14000
	s_nop 0
	v_addc_co_u32_e32 v5, vcc, 0, v3, vcc
	global_load_dword v18, v[4:5], off
	v_add_co_u32_e32 v4, vcc, s27, v2
	s_mov_b32 s27, 0x16000
	s_nop 0
	v_addc_co_u32_e32 v5, vcc, 0, v3, vcc
	global_load_dword v19, v[4:5], off
	v_add_co_u32_e32 v4, vcc, s27, v2
	s_mov_b32 s27, 0x18000
	s_nop 0
	v_addc_co_u32_e32 v5, vcc, 0, v3, vcc
	global_load_dword v20, v[4:5], off
	v_add_co_u32_e32 v4, vcc, s27, v2
	s_mov_b32 s27, 0x1a000
	s_nop 0
	v_addc_co_u32_e32 v5, vcc, 0, v3, vcc
	global_load_dword v21, v[4:5], off
	v_add_co_u32_e32 v4, vcc, s27, v2
	s_mov_b32 s27, 0x1c000
	s_nop 0
	v_addc_co_u32_e32 v5, vcc, 0, v3, vcc
	global_load_dword v22, v[4:5], off
	v_add_co_u32_e32 v4, vcc, s27, v2
	s_mov_b32 s27, 0x1e000
	s_nop 0
	v_addc_co_u32_e32 v5, vcc, 0, v3, vcc
	global_load_dword v23, v[4:5], off
	v_add_co_u32_e32 v4, vcc, s27, v2
	s_mov_b32 s27, 0x22000
	s_nop 0
	v_addc_co_u32_e32 v5, vcc, 0, v3, vcc
	global_load_dword v24, v[4:5], off
	v_add_co_u32_e32 v4, vcc, s36, v2
	s_lshl_b32 s1, s1, 1
	s_nop 0
	v_addc_co_u32_e32 v5, vcc, 0, v3, vcc
	global_load_dword v25, v[4:5], off
	v_add_co_u32_e32 v4, vcc, s27, v2
	s_mov_b32 s27, 0x24000
	s_nop 0
	v_addc_co_u32_e32 v5, vcc, 0, v3, vcc
	global_load_dword v26, v[4:5], off
	v_add_co_u32_e32 v4, vcc, s27, v2
	s_mov_b32 s27, 0x26000
	s_nop 0
	v_addc_co_u32_e32 v5, vcc, 0, v3, vcc
	global_load_dword v27, v[4:5], off
	v_add_co_u32_e32 v4, vcc, s27, v2
	s_mov_b32 s27, 0x28000
	s_nop 0
	v_addc_co_u32_e32 v5, vcc, 0, v3, vcc
	global_load_dword v28, v[4:5], off
	v_add_co_u32_e32 v4, vcc, s27, v2
	s_mov_b32 s27, 0x2a000
	s_nop 0
	v_addc_co_u32_e32 v5, vcc, 0, v3, vcc
	global_load_dword v29, v[4:5], off
	v_add_co_u32_e32 v4, vcc, s27, v2
	s_mov_b32 s27, 0x2c000
	s_nop 0
	v_addc_co_u32_e32 v5, vcc, 0, v3, vcc
	global_load_dword v30, v[4:5], off
	v_add_co_u32_e32 v4, vcc, s27, v2
	s_mov_b32 s27, 0x2e000
	s_nop 0
	v_addc_co_u32_e32 v5, vcc, 0, v3, vcc
	global_load_dword v31, v[4:5], off
	v_add_co_u32_e32 v4, vcc, s27, v2
	s_mov_b32 s27, 0x30000
	s_nop 0
	v_addc_co_u32_e32 v5, vcc, 0, v3, vcc
	global_load_dword v32, v[4:5], off
	v_add_co_u32_e32 v4, vcc, s27, v2
	s_mov_b32 s27, 0x32000
	s_nop 0
	v_addc_co_u32_e32 v5, vcc, 0, v3, vcc
	global_load_dword v33, v[4:5], off
	v_add_co_u32_e32 v4, vcc, s27, v2
	s_mov_b32 s27, 0x34000
	s_nop 0
	v_addc_co_u32_e32 v5, vcc, 0, v3, vcc
	global_load_dword v34, v[4:5], off
	v_add_co_u32_e32 v4, vcc, s27, v2
	s_mov_b32 s27, 0x36000
	s_nop 0
	v_addc_co_u32_e32 v5, vcc, 0, v3, vcc
	global_load_dword v35, v[4:5], off
	v_add_co_u32_e32 v4, vcc, s27, v2
	s_mov_b32 s27, 0x38000
	s_nop 0
	v_addc_co_u32_e32 v5, vcc, 0, v3, vcc
	global_load_dword v36, v[4:5], off
	v_add_co_u32_e32 v4, vcc, s27, v2
	s_mov_b32 s27, 0x3a000
	s_nop 0
	v_addc_co_u32_e32 v5, vcc, 0, v3, vcc
	global_load_dword v37, v[4:5], off
	v_add_co_u32_e32 v4, vcc, s27, v2
	s_mov_b32 s27, 0x3c000
	s_nop 0
	v_addc_co_u32_e32 v5, vcc, 0, v3, vcc
	global_load_dword v38, v[4:5], off
	v_add_co_u32_e32 v4, vcc, s27, v2
	s_mov_b32 s27, 0x3e000
	s_nop 0
	v_addc_co_u32_e32 v5, vcc, 0, v3, vcc
	v_add_co_u32_e32 v2, vcc, s27, v2
	global_load_dword v4, v[4:5], off
	s_nop 0
	v_addc_co_u32_e32 v3, vcc, 0, v3, vcc
	global_load_dword v2, v[2:3], off
	s_movk_i32 s27, 0x84
	v_lshlrev_b32_e32 v3, 2, v8
	v_mul_lo_u32 v5, v9, s27
	v_add3_u32 v3, s56, v3, v5
	s_waitcnt vmcnt(0)
; #define LAS __attribute__((address_space(3)))
; __device__ __forceinline__ unsigned pk2(float lo, float hi) { f32x2 v = {lo, hi}; bf16x2_t b = __builtin_convertvector(v, bf16x2_t); return __builtin_bit_cast(unsigned, b); }
; __device__ __forceinline__ void conv_item(const float* W, int K, int Nsrc, int Ndst, const float* ksc, bf16* WT, int map, int item, LAS float* scr, int lane) {
;     ...
;     for (int i = 0; i < 32; ++i) scr[(2 * i + (lane >> 5)) * 33 + (lane & 31)] = (sc >= 0) ? wv[i] : 0.f;
;     asm volatile("s_waitcnt lgkmcnt(0)" ::: "memory");
;     const int c = lane & 7;
; #pragma unroll
;     for (int j = 0; j < 4; ++j) { const int n = (lane >> 3) + 8 * j; const LAS float* s = scr + (8 * c) * 33 + n;
;         u32x4 o; o.x = pk2(s[0 * 33], s[1 * 33]); o.y = pk2(s[2 * 33], s[3 * 33]); o.z = pk2(s[4 * 33], s[5 * 33]); o.w = pk2(s[6 * 33], s[7 * 33]);
;         *(u32x4*)(WT + (size_t)(n0 + n) * K + k0 + 8 * c) = o; }
;     asm volatile("s_waitcnt lgkmcnt(0)" ::: "memory");
	ds_write2_b32 v3, v0, v10 offset1:66
	ds_write2_b32 v3, v11, v12 offset0:132 offset1:198
	v_add_u32_e32 v0, 0x400, v3
	ds_write2_b32 v0, v13, v14 offset0:8 offset1:74
	ds_write2_b32 v0, v15, v16 offset0:140 offset1:206
	v_add_u32_e32 v0, 0x800, v3
	ds_write2_b32 v0, v17, v18 offset0:16 offset1:82
	ds_write2_b32 v0, v19, v20 offset0:148 offset1:214
	v_add_u32_e32 v0, 0xc00, v3
	ds_write2_b32 v0, v21, v22 offset0:24 offset1:90
	ds_write2_b32 v0, v23, v24 offset0:156 offset1:222
	v_add_u32_e32 v0, 0x1000, v3
	ds_write2_b32 v0, v25, v26 offset0:32 offset1:98
	ds_write2_b32 v0, v27, v28 offset0:164 offset1:230
	v_add_u32_e32 v0, 0x1400, v3
	ds_write2_b32 v0, v29, v30 offset0:40 offset1:106
	ds_write2_b32 v0, v31, v32 offset0:172 offset1:238
	v_add_u32_e32 v0, 0x1800, v3
	ds_write2_b32 v0, v33, v34 offset0:48 offset1:114
	ds_write2_b32 v0, v35, v36 offset0:180 offset1:246
	v_add_u32_e32 v0, 0x1c00, v3
	ds_write2_b32 v0, v37, v38 offset0:56 offset1:122
	ds_write2_b32 v0, v4, v2 offset0:188 offset1:254
	v_lshlrev_b32_e32 v0, 3, v7
	v_and_b32_e32 v0, 56, v0
	s_add_u32 s52, s58, s1
	v_ashrrev_i32_e32 v26, 3, v7
	v_mul_u32_u24_e32 v4, 0x84, v0
	s_addc_u32 s53, s59, 0
	v_lshlrev_b32_e32 v0, 1, v0
	v_lshl_add_u64 v[2:3], s[52:53], 0, v[0:1]
	v_lshlrev_b32_e32 v0, 2, v26
	s_waitcnt lgkmcnt(0)
	v_add3_u32 v0, s56, v4, v0
	ds_read2_b32 v[10:11], v0 offset0:33 offset1:41
	ds_read2_b32 v[12:13], v0 offset1:8
	ds_read2_b32 v[14:15], v0 offset0:66 offset1:74
	ds_read2_b32 v[16:17], v0 offset0:99 offset1:107
	ds_read2_b32 v[18:19], v0 offset0:132 offset1:140
	ds_read2_b32 v[20:21], v0 offset0:165 offset1:173
	ds_read2_b32 v[22:23], v0 offset0:198 offset1:206
	ds_read2_b32 v[24:25], v0 offset0:231 offset1:239
	v_add_u32_e32 v26, s0, v26
	s_mov_b64 s[52:53], 0x2400000
	v_ashrrev_i32_e32 v27, 31, v26
	v_lshl_add_u64 v[8:9], v[2:3], 0, s[52:53]
	v_lshlrev_b64 v[28:29], 13, v[26:27]
	s_waitcnt lgkmcnt(6)
	v_cvt_pk_bf16_f32 v2, v12, v10
	s_waitcnt lgkmcnt(4)
	v_cvt_pk_bf16_f32 v3, v14, v16
	s_waitcnt lgkmcnt(2)
	v_cvt_pk_bf16_f32 v4, v18, v20
	s_waitcnt lgkmcnt(0)
	v_cvt_pk_bf16_f32 v5, v22, v24
	v_lshl_add_u64 v[28:29], v[8:9], 0, v[28:29]
	v_add_u32_e32 v10, 8, v26
	global_store_dwordx4 v[28:29], v[2:5], off
	v_add_u32_e32 v28, 16, v26
	v_ashrrev_i32_e32 v29, 31, v28
	v_cvt_pk_bf16_f32 v2, v13, v11
	v_ashrrev_i32_e32 v11, 31, v10
	v_lshlrev_b64 v[10:11], 13, v[10:11]
	v_cvt_pk_bf16_f32 v3, v15, v17
	v_cvt_pk_bf16_f32 v4, v19, v21
	v_cvt_pk_bf16_f32 v5, v23, v25
	v_lshl_add_u64 v[10:11], v[8:9], 0, v[10:11]
	global_store_dwordx4 v[10:11], v[2:5], off
	ds_read2_b32 v[10:11], v0 offset0:49 offset1:57
	ds_read2_b32 v[12:13], v0 offset0:16 offset1:24
	ds_read2_b32 v[14:15], v0 offset0:82 offset1:90
	ds_read2_b32 v[16:17], v0 offset0:115 offset1:123
	ds_read2_b32 v[18:19], v0 offset0:148 offset1:156
	ds_read2_b32 v[20:21], v0 offset0:181 offset1:189
	ds_read2_b32 v[22:23], v0 offset0:214 offset1:222
	ds_read2_b32 v[24:25], v0 offset0:247 offset1:255
	v_lshlrev_b64 v[28:29], 13, v[28:29]
	s_waitcnt lgkmcnt(6)
	v_cvt_pk_bf16_f32 v2, v12, v10
	s_waitcnt lgkmcnt(4)
	v_cvt_pk_bf16_f32 v3, v14, v16
	s_waitcnt lgkmcnt(2)
	v_cvt_pk_bf16_f32 v4, v18, v20
	s_waitcnt lgkmcnt(0)
	v_cvt_pk_bf16_f32 v5, v22, v24
	v_lshl_add_u64 v[28:29], v[8:9], 0, v[28:29]
	v_add_u32_e32 v10, 24, v26
	global_store_dwordx4 v[28:29], v[2:5], off
	s_nop 1
	v_cvt_pk_bf16_f32 v2, v13, v11
	v_ashrrev_i32_e32 v11, 31, v10
	v_lshlrev_b64 v[10:11], 13, v[10:11]
	v_cvt_pk_bf16_f32 v3, v15, v17
	v_cvt_pk_bf16_f32 v4, v19, v21
	v_cvt_pk_bf16_f32 v5, v23, v25
	v_lshl_add_u64 v[8:9], v[8:9], 0, v[10:11]
	global_store_dwordx4 v[8:9], v[2:5], off
	s_waitcnt lgkmcnt(0)

; __global__ void __launch_bounds__(512, 2) fwd_kernel(Args a) {
;     ...
;                     if (tid == 0) tkc[0] = G + (int)nxc;
.LBB0_514:
	s_add_i32 s44, 0, 0x20000
	s_waitcnt vmcnt(4)
	v_add_u32_e32 v0, s26, v6
	v_mov_b32_e32 v2, s44
	ds_write_b32 v2, v0
	s_branch .LBB0_441
